# MLA fast path: per-tile running-max chains removed; the lazy rescale is triggered by the previous tile's row partial sum (> 2^10) with an integer log2 shift from v_frexp_exp; same exp/sum/MFMA math ot
# speedup vs baseline: 1.0225x; 1.0112x over previous
.Lmla_fast_nodma:
	s_waitcnt lgkmcnt(0)
	v_mfma_f32_32x32x16_bf16 v[50:65], v[194:197], v[74:77], v[234:249]
	ds_read_b128 v[194:197], v0 offset:6656
	v_add_f32_e32 v254, v202, v203
	v_add_f32_e32 v255, v204, v205
	v_add_f32_e32 v254, v254, v206
	v_add_f32_e32 v255, v255, v207
	v_add_f32_e32 v254, v254, v208
	v_add_f32_e32 v255, v255, v209
	v_mfma_f32_32x32x16_bf16 v[50:65], v[150:153], v[78:81], v[50:65]
	ds_read_b128 v[150:153], v0 offset:6688
	v_add_f32_e32 v254, v254, v210
	v_add_f32_e32 v255, v255, v211
	v_add_f32_e32 v254, v254, v212
	v_add_f32_e32 v255, v255, v213
	v_add_f32_e32 v254, v254, v214
	v_add_f32_e32 v255, v255, v215
	v_mfma_f32_32x32x16_bf16 v[50:65], v[158:161], v[82:85], v[50:65]
	ds_read_b128 v[158:161], v0 offset:6720
	v_add_f32_e32 v254, v254, v216
	v_add_f32_e32 v255, v255, v217
	v_add_f32_e32 v254, v254, v218
	v_add_f32_e32 v255, v255, v219
	v_add_f32_e32 v254, v254, v220
	v_mfma_f32_32x32x16_bf16 v[50:65], v[162:165], v[86:89], v[50:65]
	ds_read_b128 v[162:165], v0 offset:6752
	v_add_f32_e32 v255, v255, v221
	v_add_f32_e32 v254, v254, v222
	v_add_f32_e32 v255, v255, v223
	v_add_f32_e32 v254, v254, v224
	v_add_f32_e32 v255, v255, v225
	v_mfma_f32_32x32x16_bf16 v[50:65], v[174:177], v[90:93], v[50:65]
	ds_read_b128 v[174:177], v0 offset:6784
	v_add_f32_e32 v254, v254, v226
	v_add_f32_e32 v255, v255, v227
	v_add_f32_e32 v254, v254, v228
	v_add_f32_e32 v255, v255, v229
	v_add_f32_e32 v254, v254, v230
	v_mfma_f32_32x32x16_bf16 v[50:65], v[178:181], v[94:97], v[50:65]
	ds_read_b128 v[178:181], v0 offset:6816
	v_add_f32_e32 v255, v255, v231
	v_add_f32_e32 v254, v254, v232
	v_add_f32_e32 v255, v255, v233
	v_add_f32_e32 v254, v254, v255
	v_add_f32_e32 v147, v147, v254
	s_waitcnt lgkmcnt(5)
	v_mfma_f32_32x32x16_bf16 v[34:49], v[194:197], v[74:77], v[234:249]
	ds_read_b64_tr_b16 v[126:127], v142 offset:13312
	ds_read_b64_tr_b16 v[128:129], v142 offset:14848
	ds_read_b64_tr_b16 v[124:125], v142 offset:14912
	ds_read_b64_tr_b16 v[122:123], v142 offset:13376
	s_waitcnt lgkmcnt(8)
	v_mfma_f32_32x32x16_bf16 v[34:49], v[150:153], v[78:81], v[34:49]
	ds_read_b64_tr_b16 v[118:119], v142 offset:16384
	ds_read_b64_tr_b16 v[120:121], v142 offset:17920
	ds_read_b64_tr_b16 v[116:117], v142 offset:17984
	ds_read_b64_tr_b16 v[114:115], v142 offset:16448
	s_waitcnt lgkmcnt(11)
	v_mfma_f32_32x32x16_bf16 v[34:49], v[158:161], v[82:85], v[34:49]
	ds_read_b64_tr_b16 v[110:111], v142 offset:19456
	ds_read_b64_tr_b16 v[112:113], v142 offset:20992
	ds_read_b64_tr_b16 v[108:109], v142 offset:21056
	ds_read_b64_tr_b16 v[106:107], v142 offset:19520
	s_waitcnt lgkmcnt(11)
	v_mfma_f32_32x32x16_bf16 v[34:49], v[162:165], v[86:89], v[34:49]
	ds_read_b64_tr_b16 v[102:103], v142 offset:22528
	ds_read_b64_tr_b16 v[104:105], v142 offset:24064
	ds_read_b64_tr_b16 v[100:101], v142 offset:24128
	ds_read_b64_tr_b16 v[98:99], v142 offset:22592
	v_mfma_f32_32x32x16_bf16 v[34:49], v[174:177], v[90:93], v[34:49]
	v_exp_f32_e32 v202, v50
	v_mfma_f32_32x32x16_bf16 v[34:49], v[178:181], v[94:97], v[34:49]
	s_and_b64 vcc, exec, s[16:17]
	s_cbranch_vccz .Lmla_fast_nostag
	s_waitcnt vmcnt(0) lgkmcnt(0)
	s_barrier
	s_mov_b64 s[16:17], 0
.Lmla_fast_nostag:
	v_exp_f32_e32 v203, v51
	v_exp_f32_e32 v204, v52
	v_exp_f32_e32 v205, v53
	v_exp_f32_e32 v206, v54
	v_exp_f32_e32 v207, v55
	v_exp_f32_e32 v208, v56
	v_exp_f32_e32 v209, v57
	v_exp_f32_e32 v210, v58
	v_exp_f32_e32 v211, v59
	v_exp_f32_e32 v212, v60
	v_exp_f32_e32 v213, v61
	v_exp_f32_e32 v214, v62
	v_exp_f32_e32 v215, v63
	v_exp_f32_e32 v216, v64
	v_exp_f32_e32 v217, v65
	v_cmp_lt_f32_e32 vcc, 0x44800000, v254
	s_cbranch_vccnz .Lmla_fast_rescale

.Lmla_fast_rescale:
	v_frexp_exp_i32_f32_e32 v0, v254
	v_cvt_f32_i32_e32 v0, v0
	v_xor_b32_e32 v149, 32, v187
	v_cmp_lt_i32_e32 vcc, v149, v189
	s_nop 1
	v_cndmask_b32_e32 v149, v187, v149, vcc
	v_lshlrev_b32_e32 v149, 2, v149
	ds_bpermute_b32 v149, v149, v0
	s_waitcnt lgkmcnt(0)
	v_max3_f32 v149, v0, v149, 0
	v_exp_f32_e64 v0, -v149
	v_add_f32_e32 v148, v148, v149
	v_pk_mul_f32 v[32:33], v[32:33], v[0:1] op_sel_hi:[1,0]
	v_pk_mul_f32 v[30:31], v[30:31], v[0:1] op_sel_hi:[1,0]
	v_pk_mul_f32 v[28:29], v[28:29], v[0:1] op_sel_hi:[1,0]
	v_pk_mul_f32 v[26:27], v[26:27], v[0:1] op_sel_hi:[1,0]
	v_pk_mul_f32 v[24:25], v[24:25], v[0:1] op_sel_hi:[1,0]
	v_pk_mul_f32 v[22:23], v[22:23], v[0:1] op_sel_hi:[1,0]
	v_pk_mul_f32 v[20:21], v[20:21], v[0:1] op_sel_hi:[1,0]
	v_pk_mul_f32 v[18:19], v[18:19], v[0:1] op_sel_hi:[1,0]
	v_pk_mul_f32 v[16:17], v[16:17], v[0:1] op_sel_hi:[1,0]
	v_pk_mul_f32 v[14:15], v[14:15], v[0:1] op_sel_hi:[1,0]
	v_pk_mul_f32 v[12:13], v[12:13], v[0:1] op_sel_hi:[1,0]
	v_pk_mul_f32 v[10:11], v[10:11], v[0:1] op_sel_hi:[1,0]
	v_pk_mul_f32 v[8:9], v[8:9], v[0:1] op_sel_hi:[1,0]
	v_pk_mul_f32 v[6:7], v[6:7], v[0:1] op_sel_hi:[1,0]
	v_pk_mul_f32 v[4:5], v[4:5], v[0:1] op_sel_hi:[1,0]
	v_pk_mul_f32 v[2:3], v[2:3], v[0:1] op_sel_hi:[1,0]
	v_mul_f32_e32 v147, v147, v0
	v_sub_f32_e32 v234, v234, v149
	v_sub_f32_e32 v235, v235, v149
	v_sub_f32_e32 v236, v236, v149
	v_sub_f32_e32 v237, v237, v149
	v_sub_f32_e32 v238, v238, v149
	v_sub_f32_e32 v239, v239, v149
	v_sub_f32_e32 v240, v240, v149
	v_sub_f32_e32 v241, v241, v149
	v_sub_f32_e32 v242, v242, v149
	v_sub_f32_e32 v243, v243, v149
	v_sub_f32_e32 v244, v244, v149
	v_sub_f32_e32 v245, v245, v149
	v_sub_f32_e32 v246, v246, v149
	v_sub_f32_e32 v247, v247, v149
	v_sub_f32_e32 v248, v248, v149
	v_sub_f32_e32 v249, v249, v149
	v_sub_f32_e32 v50, v50, v149
	v_sub_f32_e32 v51, v51, v149
	v_sub_f32_e32 v52, v52, v149
	v_sub_f32_e32 v53, v53, v149
	v_sub_f32_e32 v54, v54, v149
	v_sub_f32_e32 v55, v55, v149
	v_sub_f32_e32 v56, v56, v149
	v_sub_f32_e32 v57, v57, v149
	v_sub_f32_e32 v58, v58, v149
	v_sub_f32_e32 v59, v59, v149
	v_sub_f32_e32 v60, v60, v149
	v_sub_f32_e32 v61, v61, v149
	v_sub_f32_e32 v62, v62, v149
	v_sub_f32_e32 v63, v63, v149
	v_sub_f32_e32 v64, v64, v149
	v_sub_f32_e32 v65, v65, v149
	v_sub_f32_e32 v34, v34, v149
	v_sub_f32_e32 v35, v35, v149
	v_sub_f32_e32 v36, v36, v149
	v_sub_f32_e32 v37, v37, v149
	v_sub_f32_e32 v38, v38, v149
	v_sub_f32_e32 v39, v39, v149
	v_sub_f32_e32 v40, v40, v149
	v_sub_f32_e32 v41, v41, v149
	v_sub_f32_e32 v42, v42, v149
	v_sub_f32_e32 v43, v43, v149
	v_sub_f32_e32 v44, v44, v149
	v_sub_f32_e32 v45, v45, v149
	v_sub_f32_e32 v46, v46, v149
	v_sub_f32_e32 v47, v47, v149
	v_sub_f32_e32 v48, v48, v149
	v_sub_f32_e32 v49, v49, v149
	v_exp_f32_e32 v202, v50
	v_exp_f32_e32 v203, v51
	v_exp_f32_e32 v204, v52
	v_exp_f32_e32 v205, v53
	v_exp_f32_e32 v206, v54
	v_exp_f32_e32 v207, v55
	v_exp_f32_e32 v208, v56
	v_exp_f32_e32 v209, v57
	v_exp_f32_e32 v210, v58
	v_exp_f32_e32 v211, v59
	v_exp_f32_e32 v212, v60
	v_exp_f32_e32 v213, v61
	v_exp_f32_e32 v214, v62
	v_exp_f32_e32 v215, v63
	v_exp_f32_e32 v216, v64
	v_exp_f32_e32 v217, v65
	s_branch .Lmla_fast_ok
